# fused out-projection loop: last K iteration issues no next-tile stage loads when no tile follows; exact waits for that iteration
# baseline (speedup 1.0000x reference)
.LBB0_476:
	s_add_i32 s63, s31, 2
	s_add_u32 s38, s28, s36
	s_addc_u32 s39, s29, s37
	s_add_u32 s64, s26, s36
	s_addc_u32 s65, s27, s37
	s_add_i32 s66, 0, 0x10000
	s_cmp_eq_u32 s59, s31
	s_cselect_b32 s39, s9, s39
	s_cselect_b32 s38, s8, s38
	s_cselect_b32 s65, s35, s65
	s_cselect_b32 s64, s34, s64
	s_cselect_b32 s100, 1, 0
	s_cmp_lg_u64 s[6:7], 0
	s_cselect_b32 s100, s100, 0
	s_add_i32 s31, 0, 0x14000
	v_add_u32_e32 v160, s66, v146
	v_add_u32_e32 v176, s31, v146
	ds_read_b128 v[148:151], v160
	ds_read_b128 v[152:155], v160 offset:1024
	ds_read_b128 v[156:159], v160 offset:2048
	ds_read_b128 v[160:163], v160 offset:3072
	ds_read_b128 v[164:167], v176
	ds_read_b128 v[168:171], v176 offset:1024
	ds_read_b128 v[172:175], v176 offset:2048
	ds_read_b128 v[176:179], v176 offset:3072
	v_lshl_add_u64 v[208:209], s[28:29], 0, v[142:143]
	s_add_i32 m0, s51, 0xc000
	ds_read_b128 v[180:183], v147
	ds_read_b128 v[184:187], v147 offset:1024
	ds_read_b128 v[188:191], v147 offset:2048
	ds_read_b128 v[192:195], v147 offset:3072
	ds_read_b128 v[196:199], v147 offset:4096
	ds_read_b128 v[200:203], v147 offset:5120
	ds_read_b128 v[204:207], v147 offset:6144
	ds_read_b128 v[220:223], v147 offset:7168
	global_load_lds_dwordx4 v[208:209], off
	v_lshl_add_u64 v[208:209], s[28:29], 0, v[144:145]
	s_add_i32 m0, s51, 0xe000
	s_nop 0
	global_load_lds_dwordx4 v[208:209], off
	s_nop 0
	s_nop 0
	s_nop 0
	s_nop 0
	s_nop 0
	s_nop 0
	s_nop 0
	s_nop 0
	s_nop 0
	s_nop 0
	s_nop 0
	s_nop 0
	s_nop 0
	s_nop 0
	s_nop 0
	s_nop 0
	s_nop 0
	s_nop 0
	s_nop 0
	s_nop 0
	s_nop 0
	s_nop 0
	s_nop 0
	s_nop 0
	s_nop 0
	s_waitcnt vmcnt(8)
	s_waitcnt lgkmcnt(0)
	s_barrier
	s_waitcnt lgkmcnt(0)
	v_mfma_f32_16x16x32_bf16 v[126:129], v[148:151], v[180:183], v[126:129]
	v_mfma_f32_16x16x32_bf16 v[122:125], v[156:159], v[180:183], v[122:125]
	v_mfma_f32_16x16x32_bf16 v[110:113], v[148:151], v[188:191], v[110:113]
	v_mfma_f32_16x16x32_bf16 v[106:109], v[156:159], v[188:191], v[106:109]
	v_mfma_f32_16x16x32_bf16 v[94:97], v[148:151], v[196:199], v[94:97]
	v_mfma_f32_16x16x32_bf16 v[90:93], v[156:159], v[196:199], v[90:93]
	v_mfma_f32_16x16x32_bf16 v[78:81], v[148:151], v[204:207], v[78:81]
	v_mfma_f32_16x16x32_bf16 v[74:77], v[156:159], v[204:207], v[74:77]
	v_mfma_f32_16x16x32_bf16 v[126:129], v[152:155], v[184:187], v[126:129]
	v_mfma_f32_16x16x32_bf16 v[122:125], v[160:163], v[184:187], v[122:125]
	v_mfma_f32_16x16x32_bf16 v[110:113], v[152:155], v[192:195], v[110:113]
	v_mfma_f32_16x16x32_bf16 v[106:109], v[160:163], v[192:195], v[106:109]
	v_mfma_f32_16x16x32_bf16 v[94:97], v[152:155], v[200:203], v[94:97]
	v_mfma_f32_16x16x32_bf16 v[90:93], v[160:163], v[200:203], v[90:93]
	v_mfma_f32_16x16x32_bf16 v[78:81], v[152:155], v[220:223], v[78:81]
	v_mfma_f32_16x16x32_bf16 v[74:77], v[160:163], v[220:223], v[74:77]
	v_mfma_f32_16x16x32_bf16 v[118:121], v[164:167], v[180:183], v[118:121]
	v_mfma_f32_16x16x32_bf16 v[114:117], v[172:175], v[180:183], v[114:117]
	v_mfma_f32_16x16x32_bf16 v[102:105], v[164:167], v[188:191], v[102:105]
	v_mfma_f32_16x16x32_bf16 v[98:101], v[172:175], v[188:191], v[98:101]
	v_mfma_f32_16x16x32_bf16 v[86:89], v[164:167], v[196:199], v[86:89]
	v_mfma_f32_16x16x32_bf16 v[82:85], v[172:175], v[196:199], v[82:85]
	v_mfma_f32_16x16x32_bf16 v[70:73], v[164:167], v[204:207], v[70:73]
	v_mfma_f32_16x16x32_bf16 v[66:69], v[172:175], v[204:207], v[66:69]
	v_mfma_f32_16x16x32_bf16 v[118:121], v[168:171], v[184:187], v[118:121]
	v_mfma_f32_16x16x32_bf16 v[114:117], v[176:179], v[184:187], v[114:117]
	v_mfma_f32_16x16x32_bf16 v[102:105], v[168:171], v[192:195], v[102:105]
	v_mfma_f32_16x16x32_bf16 v[98:101], v[176:179], v[192:195], v[98:101]
	v_mfma_f32_16x16x32_bf16 v[86:89], v[168:171], v[200:203], v[86:89]
	v_mfma_f32_16x16x32_bf16 v[82:85], v[176:179], v[200:203], v[82:85]
	v_mfma_f32_16x16x32_bf16 v[70:73], v[168:171], v[220:223], v[70:73]
	v_mfma_f32_16x16x32_bf16 v[66:69], v[176:179], v[220:223], v[66:69]
	s_barrier
	s_add_i32 s66, s66, s47
	v_lshl_add_u64 v[208:209], s[64:65], 0, v[132:133]
	s_mov_b32 m0, s66
	ds_read_b128 v[180:183], v147 offset:16384
	ds_read_b128 v[184:187], v147 offset:17408
	ds_read_b128 v[188:191], v147 offset:18432
	ds_read_b128 v[192:195], v147 offset:19456
	ds_read_b128 v[196:199], v147 offset:20480
	ds_read_b128 v[200:203], v147 offset:21504
	ds_read_b128 v[204:207], v147 offset:22528
	ds_read_b128 v[220:223], v147 offset:23552
	s_bitcmp1_b32 s100, 0
	s_cbranch_scc1 .Lfe_sk0
	global_load_lds_dwordx4 v[208:209], off
.Lfe_sk0:
	s_add_i32 m0, s66, 0x2000
	v_lshl_add_u64 v[224:225], s[64:65], 0, v[136:137]
	s_add_u32 s64, s64, s45
	s_addc_u32 s65, s65, 0
	s_add_i32 s31, s31, s47
	s_bitcmp1_b32 s100, 0
	s_cbranch_scc1 .Lfe_sk1
	global_load_lds_dwordx4 v[224:225], off
.Lfe_sk1:
	v_lshl_add_u64 v[230:231], s[64:65], 0, v[132:133]
	s_mov_b32 m0, s31
	v_lshl_add_u64 v[236:237], s[64:65], 0, v[136:137]
	s_bitcmp1_b32 s100, 0
	s_cbranch_scc1 .Lfe_sk2
	global_load_lds_dwordx4 v[230:231], off
.Lfe_sk2:
	s_add_i32 m0, s31, 0x2000
	v_lshl_add_u64 v[238:239], s[38:39], 0, v[130:131]
	s_bitcmp1_b32 s100, 0
	s_cbranch_scc1 .Lfe_sk3
	global_load_lds_dwordx4 v[236:237], off
.Lfe_sk3:
	s_mov_b32 m0, s51
	v_lshl_add_u64 v[240:241], s[38:39], 0, v[134:135]
	s_bitcmp1_b32 s100, 0
	s_cbranch_scc1 .Lfe_sk4
	global_load_lds_dwordx4 v[238:239], off
.Lfe_sk4:
	s_mov_b32 m0, s52
	s_nop 0
	s_bitcmp1_b32 s100, 0
	s_cbranch_scc1 .Lfe_sk5
	global_load_lds_dwordx4 v[240:241], off
.Lfe_sk5:
	s_nop 0
	s_nop 0
	s_nop 0
	s_nop 0
	s_nop 0
	s_nop 0
	s_bitcmp1_b32 s100, 0
	s_cbranch_scc0 .Lfe_w2
	s_waitcnt vmcnt(2)
.Lfe_w2:
	s_nop 0
	s_waitcnt vmcnt(8)
	s_waitcnt lgkmcnt(0)
	s_barrier
	s_waitcnt lgkmcnt(0)
	v_mfma_f32_16x16x32_bf16 v[62:65], v[148:151], v[180:183], v[62:65]
	v_mfma_f32_16x16x32_bf16 v[58:61], v[156:159], v[180:183], v[58:61]
	v_mfma_f32_16x16x32_bf16 v[46:49], v[148:151], v[188:191], v[46:49]
	v_mfma_f32_16x16x32_bf16 v[42:45], v[156:159], v[188:191], v[42:45]
	v_mfma_f32_16x16x32_bf16 v[30:33], v[148:151], v[196:199], v[30:33]
	v_mfma_f32_16x16x32_bf16 v[26:29], v[156:159], v[196:199], v[26:29]
	v_mfma_f32_16x16x32_bf16 v[14:17], v[148:151], v[204:207], v[14:17]
	v_mfma_f32_16x16x32_bf16 v[10:13], v[156:159], v[204:207], v[10:13]
	v_mfma_f32_16x16x32_bf16 v[62:65], v[152:155], v[184:187], v[62:65]
	v_mfma_f32_16x16x32_bf16 v[58:61], v[160:163], v[184:187], v[58:61]
	v_mfma_f32_16x16x32_bf16 v[46:49], v[152:155], v[192:195], v[46:49]
	v_mfma_f32_16x16x32_bf16 v[42:45], v[160:163], v[192:195], v[42:45]
	v_mfma_f32_16x16x32_bf16 v[30:33], v[152:155], v[200:203], v[30:33]
	v_mfma_f32_16x16x32_bf16 v[26:29], v[160:163], v[200:203], v[26:29]
	v_mfma_f32_16x16x32_bf16 v[14:17], v[152:155], v[220:223], v[14:17]
	v_mfma_f32_16x16x32_bf16 v[10:13], v[160:163], v[220:223], v[10:13]
	v_mfma_f32_16x16x32_bf16 v[54:57], v[164:167], v[180:183], v[54:57]
	v_mfma_f32_16x16x32_bf16 v[50:53], v[172:175], v[180:183], v[50:53]
	v_mfma_f32_16x16x32_bf16 v[38:41], v[164:167], v[188:191], v[38:41]
	v_mfma_f32_16x16x32_bf16 v[34:37], v[172:175], v[188:191], v[34:37]
	v_mfma_f32_16x16x32_bf16 v[22:25], v[164:167], v[196:199], v[22:25]
	v_mfma_f32_16x16x32_bf16 v[18:21], v[172:175], v[196:199], v[18:21]
	v_mfma_f32_16x16x32_bf16 v[6:9], v[164:167], v[204:207], v[6:9]
	v_mfma_f32_16x16x32_bf16 v[2:5], v[172:175], v[204:207], v[2:5]
	v_mfma_f32_16x16x32_bf16 v[54:57], v[168:171], v[184:187], v[54:57]
	v_mfma_f32_16x16x32_bf16 v[50:53], v[176:179], v[184:187], v[50:53]
	v_mfma_f32_16x16x32_bf16 v[38:41], v[168:171], v[192:195], v[38:41]
	v_mfma_f32_16x16x32_bf16 v[34:37], v[176:179], v[192:195], v[34:37]
	v_mfma_f32_16x16x32_bf16 v[22:25], v[168:171], v[200:203], v[22:25]
	v_mfma_f32_16x16x32_bf16 v[18:21], v[176:179], v[200:203], v[18:21]
	v_mfma_f32_16x16x32_bf16 v[6:9], v[168:171], v[220:223], v[6:9]
	v_mfma_f32_16x16x32_bf16 v[2:5], v[176:179], v[220:223], v[2:5]
	s_barrier
	s_add_i32 s31, 0, 0x18000
	s_add_i32 s64, 0, 0x1c000
	v_add_u32_e32 v160, s31, v146
	v_add_u32_e32 v176, s64, v146
	ds_read_b128 v[148:151], v160
	ds_read_b128 v[152:155], v160 offset:1024
	ds_read_b128 v[156:159], v160 offset:2048
	ds_read_b128 v[160:163], v160 offset:3072
	ds_read_b128 v[164:167], v176
	ds_read_b128 v[168:171], v176 offset:1024
	ds_read_b128 v[172:175], v176 offset:2048
	ds_read_b128 v[176:179], v176 offset:3072
	s_add_u32 s38, s38, s45
	s_addc_u32 s39, s39, 0
	s_mov_b32 m0, s53
	v_lshl_add_u64 v[242:243], s[38:39], 0, v[130:131]
	ds_read_b128 v[180:183], v147 offset:32768
	ds_read_b128 v[184:187], v147 offset:33792
	ds_read_b128 v[188:191], v147 offset:34816
	ds_read_b128 v[192:195], v147 offset:35840
	ds_read_b128 v[196:199], v147 offset:36864
	ds_read_b128 v[200:203], v147 offset:37888
	ds_read_b128 v[204:207], v147 offset:38912
	ds_read_b128 v[220:223], v147 offset:39936
	s_bitcmp1_b32 s100, 0
	s_cbranch_scc1 .Lfe_sk6
	global_load_lds_dwordx4 v[242:243], off
.Lfe_sk6:
	v_lshl_add_u64 v[242:243], s[38:39], 0, v[134:135]
	s_mov_b32 m0, s54
	s_nop 0
	s_bitcmp1_b32 s100, 0
	s_cbranch_scc1 .Lfe_sk7
	global_load_lds_dwordx4 v[242:243], off
.Lfe_sk7:
	s_nop 0
	s_nop 0
	s_nop 0
	s_nop 0
	s_nop 0
	s_nop 0
	s_nop 0
	s_nop 0
	s_bitcmp1_b32 s100, 0
	s_cbranch_scc0 .Lfe_w4
	s_waitcnt vmcnt(0)
.Lfe_w4:
	s_nop 0
	s_nop 0
	s_nop 0
	s_nop 0
	s_nop 0
	s_nop 0
	s_nop 0
	s_nop 0
	s_nop 0
	s_waitcnt vmcnt(8)
	s_waitcnt lgkmcnt(0)
	s_barrier
	s_waitcnt lgkmcnt(0)
	v_mfma_f32_16x16x32_bf16 v[126:129], v[148:151], v[180:183], v[126:129]
	v_mfma_f32_16x16x32_bf16 v[122:125], v[156:159], v[180:183], v[122:125]
	v_mfma_f32_16x16x32_bf16 v[110:113], v[148:151], v[188:191], v[110:113]
	v_mfma_f32_16x16x32_bf16 v[106:109], v[156:159], v[188:191], v[106:109]
	v_mfma_f32_16x16x32_bf16 v[94:97], v[148:151], v[196:199], v[94:97]
	v_mfma_f32_16x16x32_bf16 v[90:93], v[156:159], v[196:199], v[90:93]
	v_mfma_f32_16x16x32_bf16 v[78:81], v[148:151], v[204:207], v[78:81]
	v_mfma_f32_16x16x32_bf16 v[74:77], v[156:159], v[204:207], v[74:77]
	v_mfma_f32_16x16x32_bf16 v[126:129], v[152:155], v[184:187], v[126:129]
	v_mfma_f32_16x16x32_bf16 v[122:125], v[160:163], v[184:187], v[122:125]
	v_mfma_f32_16x16x32_bf16 v[110:113], v[152:155], v[192:195], v[110:113]
	v_mfma_f32_16x16x32_bf16 v[106:109], v[160:163], v[192:195], v[106:109]
	v_mfma_f32_16x16x32_bf16 v[94:97], v[152:155], v[200:203], v[94:97]
	v_mfma_f32_16x16x32_bf16 v[90:93], v[160:163], v[200:203], v[90:93]
	v_mfma_f32_16x16x32_bf16 v[78:81], v[152:155], v[220:223], v[78:81]
	v_mfma_f32_16x16x32_bf16 v[74:77], v[160:163], v[220:223], v[74:77]
	v_mfma_f32_16x16x32_bf16 v[118:121], v[164:167], v[180:183], v[118:121]
	v_mfma_f32_16x16x32_bf16 v[114:117], v[172:175], v[180:183], v[114:117]
	v_mfma_f32_16x16x32_bf16 v[102:105], v[164:167], v[188:191], v[102:105]
	v_mfma_f32_16x16x32_bf16 v[98:101], v[172:175], v[188:191], v[98:101]
	v_mfma_f32_16x16x32_bf16 v[86:89], v[164:167], v[196:199], v[86:89]
	v_mfma_f32_16x16x32_bf16 v[82:85], v[172:175], v[196:199], v[82:85]
	v_mfma_f32_16x16x32_bf16 v[70:73], v[164:167], v[204:207], v[70:73]
	v_mfma_f32_16x16x32_bf16 v[66:69], v[172:175], v[204:207], v[66:69]
	v_mfma_f32_16x16x32_bf16 v[118:121], v[168:171], v[184:187], v[118:121]
	v_mfma_f32_16x16x32_bf16 v[114:117], v[176:179], v[184:187], v[114:117]
	v_mfma_f32_16x16x32_bf16 v[102:105], v[168:171], v[192:195], v[102:105]
	v_mfma_f32_16x16x32_bf16 v[98:101], v[176:179], v[192:195], v[98:101]
	v_mfma_f32_16x16x32_bf16 v[86:89], v[168:171], v[200:203], v[86:89]
	v_mfma_f32_16x16x32_bf16 v[82:85], v[176:179], v[200:203], v[82:85]
	v_mfma_f32_16x16x32_bf16 v[70:73], v[168:171], v[220:223], v[70:73]
	v_mfma_f32_16x16x32_bf16 v[66:69], v[176:179], v[220:223], v[66:69]
	s_barrier
	s_add_i32 s31, s31, s47
	v_lshl_add_u64 v[208:209], v[208:209], 0, s[96:97]
	s_mov_b32 m0, s31
	ds_read_b128 v[180:183], v147 offset:49152
	ds_read_b128 v[184:187], v147 offset:50176
	ds_read_b128 v[188:191], v147 offset:51200
	ds_read_b128 v[192:195], v147 offset:52224
	ds_read_b128 v[196:199], v147 offset:53248
	ds_read_b128 v[200:203], v147 offset:54272
	ds_read_b128 v[204:207], v147 offset:55296
	ds_read_b128 v[220:223], v147 offset:56320
	s_bitcmp1_b32 s100, 0
	s_cbranch_scc1 .Lfe_sk8
	global_load_lds_dwordx4 v[208:209], off
.Lfe_sk8:
	v_lshl_add_u64 v[208:209], v[224:225], 0, s[96:97]
	s_add_i32 m0, s31, 0x2000
	s_add_i32 s31, s64, s47
	s_bitcmp1_b32 s100, 0
	s_cbranch_scc1 .Lfe_sk9
	global_load_lds_dwordx4 v[208:209], off
.Lfe_sk9:
	v_lshl_add_u64 v[208:209], v[230:231], 0, s[96:97]
	s_mov_b32 m0, s31
	s_nop 0
	s_bitcmp1_b32 s100, 0
	s_cbranch_scc1 .Lfe_sk10
	global_load_lds_dwordx4 v[208:209], off
.Lfe_sk10:
	v_lshl_add_u64 v[208:209], v[236:237], 0, s[96:97]
	s_add_i32 m0, s31, 0x2000
	s_nop 0
	s_bitcmp1_b32 s100, 0
	s_cbranch_scc1 .Lfe_sk11
	global_load_lds_dwordx4 v[208:209], off
.Lfe_sk11:
	v_lshl_add_u64 v[208:209], v[238:239], 0, s[96:97]
	s_mov_b32 m0, s57
	s_nop 0
	s_bitcmp1_b32 s100, 0
	s_cbranch_scc1 .Lfe_sk12
	global_load_lds_dwordx4 v[208:209], off
.Lfe_sk12:
	v_lshl_add_u64 v[208:209], v[240:241], 0, s[96:97]
	s_mov_b32 m0, s58
	s_nop 0
	s_bitcmp1_b32 s100, 0
	s_cbranch_scc1 .Lfe_sk13
	global_load_lds_dwordx4 v[208:209], off
.Lfe_sk13:
	s_nop 0
	s_nop 0
	s_nop 0
	s_nop 0
	s_nop 0
	s_nop 0
	s_nop 0
	s_nop 0
	s_nop 0
	s_waitcnt vmcnt(8)
	s_waitcnt lgkmcnt(0)
	s_barrier
	s_waitcnt lgkmcnt(0)
	v_mfma_f32_16x16x32_bf16 v[62:65], v[148:151], v[180:183], v[62:65]
	v_mfma_f32_16x16x32_bf16 v[58:61], v[156:159], v[180:183], v[58:61]
	v_mfma_f32_16x16x32_bf16 v[46:49], v[148:151], v[188:191], v[46:49]
	v_mfma_f32_16x16x32_bf16 v[42:45], v[156:159], v[188:191], v[42:45]
	v_mfma_f32_16x16x32_bf16 v[30:33], v[148:151], v[196:199], v[30:33]
	v_mfma_f32_16x16x32_bf16 v[26:29], v[156:159], v[196:199], v[26:29]
	v_mfma_f32_16x16x32_bf16 v[14:17], v[148:151], v[204:207], v[14:17]
	v_mfma_f32_16x16x32_bf16 v[10:13], v[156:159], v[204:207], v[10:13]
	v_mfma_f32_16x16x32_bf16 v[62:65], v[152:155], v[184:187], v[62:65]
	v_mfma_f32_16x16x32_bf16 v[58:61], v[160:163], v[184:187], v[58:61]
	v_mfma_f32_16x16x32_bf16 v[46:49], v[152:155], v[192:195], v[46:49]
	v_mfma_f32_16x16x32_bf16 v[42:45], v[160:163], v[192:195], v[42:45]
	v_mfma_f32_16x16x32_bf16 v[30:33], v[152:155], v[200:203], v[30:33]
	v_mfma_f32_16x16x32_bf16 v[26:29], v[160:163], v[200:203], v[26:29]
	v_mfma_f32_16x16x32_bf16 v[14:17], v[152:155], v[220:223], v[14:17]
	v_mfma_f32_16x16x32_bf16 v[10:13], v[160:163], v[220:223], v[10:13]
	v_mfma_f32_16x16x32_bf16 v[54:57], v[164:167], v[180:183], v[54:57]
	v_mfma_f32_16x16x32_bf16 v[50:53], v[172:175], v[180:183], v[50:53]
	v_mfma_f32_16x16x32_bf16 v[38:41], v[164:167], v[188:191], v[38:41]
	v_mfma_f32_16x16x32_bf16 v[34:37], v[172:175], v[188:191], v[34:37]
	v_mfma_f32_16x16x32_bf16 v[22:25], v[164:167], v[196:199], v[22:25]
	v_mfma_f32_16x16x32_bf16 v[18:21], v[172:175], v[196:199], v[18:21]
	v_mfma_f32_16x16x32_bf16 v[6:9], v[164:167], v[204:207], v[6:9]
	v_mfma_f32_16x16x32_bf16 v[2:5], v[172:175], v[204:207], v[2:5]
	v_mfma_f32_16x16x32_bf16 v[54:57], v[168:171], v[184:187], v[54:57]
	v_mfma_f32_16x16x32_bf16 v[50:53], v[176:179], v[184:187], v[50:53]
	v_mfma_f32_16x16x32_bf16 v[38:41], v[168:171], v[192:195], v[38:41]
	v_mfma_f32_16x16x32_bf16 v[34:37], v[176:179], v[192:195], v[34:37]
	v_mfma_f32_16x16x32_bf16 v[22:25], v[168:171], v[200:203], v[22:25]
	v_mfma_f32_16x16x32_bf16 v[18:21], v[176:179], v[200:203], v[18:21]
	v_mfma_f32_16x16x32_bf16 v[6:9], v[168:171], v[220:223], v[6:9]
	v_mfma_f32_16x16x32_bf16 v[2:5], v[176:179], v[220:223], v[2:5]
	s_barrier
	s_add_u32 s36, s36, 0x100
	s_addc_u32 s37, s37, 0
	v_lshl_add_u64 v[144:145], v[144:145], 0, s[2:3]
	v_lshl_add_u64 v[142:143], v[142:143], 0, s[2:3]
	s_cmp_ge_u32 s63, s56
	s_mov_b32 s31, s63
	s_cbranch_scc0 .LBB0_476
	s_and_b64 vcc, exec, s[6:7]
	s_cbranch_vccnz .LBB0_464
	v_mov_b32_e32 v2, 0
	s_mov_b32 s55, s61
	s_mov_b32 s50, s62
	s_mov_b64 s[26:27], s[34:35]
	s_mov_b64 s[28:29], s[8:9]
	s_mov_b32 s60, s30
	v_mov_b32_e32 v3, v2
	v_mov_b32_e32 v4, v2
	v_mov_b32_e32 v5, v2
	v_mov_b32_e32 v6, v2
	v_mov_b32_e32 v7, v2
	v_mov_b32_e32 v8, v2
	v_mov_b32_e32 v9, v2
	v_mov_b32_e32 v18, v2
	v_mov_b32_e32 v19, v2
	v_mov_b32_e32 v20, v2
	v_mov_b32_e32 v21, v2
	v_mov_b32_e32 v22, v2
	v_mov_b32_e32 v23, v2
	v_mov_b32_e32 v24, v2
	v_mov_b32_e32 v25, v2
	v_mov_b32_e32 v34, v2
	v_mov_b32_e32 v35, v2
	v_mov_b32_e32 v36, v2
	v_mov_b32_e32 v37, v2
	v_mov_b32_e32 v38, v2
	v_mov_b32_e32 v39, v2
	v_mov_b32_e32 v40, v2
	v_mov_b32_e32 v41, v2
	v_mov_b32_e32 v50, v2
	v_mov_b32_e32 v51, v2
	v_mov_b32_e32 v52, v2
	v_mov_b32_e32 v53, v2
	v_mov_b32_e32 v54, v2
	v_mov_b32_e32 v55, v2
	v_mov_b32_e32 v56, v2
	v_mov_b32_e32 v57, v2
	v_mov_b32_e32 v10, v2
	v_mov_b32_e32 v11, v2
	v_mov_b32_e32 v12, v2
	v_mov_b32_e32 v13, v2
	v_mov_b32_e32 v14, v2
	v_mov_b32_e32 v15, v2
	v_mov_b32_e32 v16, v2
	v_mov_b32_e32 v17, v2
	v_mov_b32_e32 v26, v2
	v_mov_b32_e32 v27, v2
	v_mov_b32_e32 v28, v2
	v_mov_b32_e32 v29, v2
	v_mov_b32_e32 v30, v2
	v_mov_b32_e32 v31, v2
	v_mov_b32_e32 v32, v2
	v_mov_b32_e32 v33, v2
	v_mov_b32_e32 v42, v2
	v_mov_b32_e32 v43, v2
	v_mov_b32_e32 v44, v2
	v_mov_b32_e32 v45, v2
	v_mov_b32_e32 v46, v2
	v_mov_b32_e32 v47, v2
	v_mov_b32_e32 v48, v2
	v_mov_b32_e32 v49, v2
	v_mov_b32_e32 v58, v2
	v_mov_b32_e32 v59, v2
	v_mov_b32_e32 v60, v2
	v_mov_b32_e32 v61, v2
	v_mov_b32_e32 v62, v2
	v_mov_b32_e32 v63, v2
	v_mov_b32_e32 v64, v2
	v_mov_b32_e32 v65, v2
	v_mov_b32_e32 v66, v2
	v_mov_b32_e32 v67, v2
	v_mov_b32_e32 v68, v2
	v_mov_b32_e32 v69, v2
	v_mov_b32_e32 v70, v2
	v_mov_b32_e32 v71, v2
	v_mov_b32_e32 v72, v2
	v_mov_b32_e32 v73, v2
	v_mov_b32_e32 v82, v2
	v_mov_b32_e32 v83, v2
	v_mov_b32_e32 v84, v2
	v_mov_b32_e32 v85, v2
	v_mov_b32_e32 v86, v2
	v_mov_b32_e32 v87, v2
	v_mov_b32_e32 v88, v2
	v_mov_b32_e32 v89, v2
	v_mov_b32_e32 v98, v2
	v_mov_b32_e32 v99, v2
	v_mov_b32_e32 v100, v2
	v_mov_b32_e32 v101, v2
	v_mov_b32_e32 v102, v2
	v_mov_b32_e32 v103, v2
	v_mov_b32_e32 v104, v2
	v_mov_b32_e32 v105, v2
	v_mov_b32_e32 v114, v2
	v_mov_b32_e32 v115, v2
	v_mov_b32_e32 v116, v2
	v_mov_b32_e32 v117, v2
	v_mov_b32_e32 v118, v2
	v_mov_b32_e32 v119, v2
	v_mov_b32_e32 v120, v2
	v_mov_b32_e32 v121, v2
	v_mov_b32_e32 v74, v2
	v_mov_b32_e32 v75, v2
	v_mov_b32_e32 v76, v2
	v_mov_b32_e32 v77, v2
	v_mov_b32_e32 v78, v2
	v_mov_b32_e32 v79, v2
	v_mov_b32_e32 v80, v2
	v_mov_b32_e32 v81, v2
	v_mov_b32_e32 v90, v2
	v_mov_b32_e32 v91, v2
	v_mov_b32_e32 v92, v2
	v_mov_b32_e32 v93, v2
	v_mov_b32_e32 v94, v2
	v_mov_b32_e32 v95, v2
	v_mov_b32_e32 v96, v2
	v_mov_b32_e32 v97, v2
	v_mov_b32_e32 v106, v2
	v_mov_b32_e32 v107, v2
	v_mov_b32_e32 v108, v2
	v_mov_b32_e32 v109, v2
	v_mov_b32_e32 v110, v2
	v_mov_b32_e32 v111, v2
	v_mov_b32_e32 v112, v2
	v_mov_b32_e32 v113, v2
	v_mov_b32_e32 v122, v2
	v_mov_b32_e32 v123, v2
	v_mov_b32_e32 v124, v2
	v_mov_b32_e32 v125, v2
	v_mov_b32_e32 v126, v2
	v_mov_b32_e32 v127, v2
	v_mov_b32_e32 v128, v2
	v_mov_b32_e32 v129, v2
	s_branch .LBB0_464
